# hg_scan prefetch addresses strength-reduced to running 64-bit row pointer plus constant steps
# speedup vs baseline: 1.0049x; 1.0049x over previous
; DI f32x16 zero16() { f32x16 z; for (int i = 0; i < 16; ++i) z[i] = 0.f; return z; }
; #define HG_PREFETCH(cn) do { \
;     _Pragma("unroll") for (int e = 0; e < 8; ++e) { const bf16_t* pr = PROJ + ROWTOK(cn, seg * 8 + e) * 8192 + h * 128; \
;       rq[e] = *(const unsigned*)(pr + 2 * kp); rf[e] = *(const unsigned*)(pr + 2048 + dir * 2048 + 2 * kp); rv[e] = pr[6144 + dh * 64 + lane]; } } while (0)
; DI void hg_scan_phase(int wvs, char* smem, const bf16_t* __restrict__ PROJ, const float* __restrict__ lbraw, bf16_t* OF, bf16_t* OB) {
;     ...
;     float lbv[2];
; #pragma unroll
;     for (int u = 0; u < 2; ++u) {
;       const int idx = dir * 2048 + h * 128 + 2 * kp + u;
;       const float l0 = lbraw[idx], l1 = lbraw[4096 + idx], l2 = lbraw[8192 + idx], l3 = lbraw[12288 + idx];
;       const float mx = fmaxf(fmaxf(l0, l1), fmaxf(l2, l3));
;       const float e0 = expf(l0 - mx), e1 = expf(l1 - mx), e2 = expf(l2 - mx), e3 = expf(l3 - mx);
;       lbv[u] = (e1 + e2) / (e0 + e1 + e2 + e3);
;     }
;     const float lb0 = lbv[0], lb1 = lbv[1];
;     bf16_t* O = dir ? OB : OF;
;     f32x16 sacc = zero16();
;     const int kb = w & 3, db = w >> 2;
;     ...
;     unsigned rq[8], rf[8]; bf16_t rv[8];
;     ...
;     __syncthreads();
;     for (int e = tid; e < 64 * SD / 2; e += NT) ((unsigned*)St)[e] = 0u;
;     HG_PREFETCH(0);
.LBB0_375:
	s_or_b64 exec, exec, s[24:25]
	v_mul_f32_e32 v8, 0x3fb8aa3b, v0
	v_fma_f32 v9, v0, s97, -v8
	v_fmac_f32_e32 v9, 0x32a5705f, v0
	v_rndne_f32_e32 v0, v8
	v_sub_f32_e32 v8, v8, v0
	v_add_f32_e32 v8, v8, v9
	v_exp_f32_e32 v8, v8
	v_cvt_i32_f32_e32 v0, v0
	s_mov_b64 s[94:95], s[12:13]
	v_readlane_b32 s12, v253, 5
	v_readlane_b32 s13, v253, 6
	v_ldexp_f32 v0, v8, v0
	v_mul_f32_e32 v8, 0x3fb8aa3b, v2
	v_fma_f32 v9, v2, s97, -v8
	v_fmac_f32_e32 v9, 0x32a5705f, v2
	v_rndne_f32_e32 v2, v8
	v_sub_f32_e32 v8, v8, v2
	v_add_f32_e32 v8, v8, v9
	v_exp_f32_e32 v8, v8
	v_cvt_i32_f32_e32 v2, v2
	v_lshlrev_b32_e32 v128, 1, v92
	v_mov_b32_e32 v17, v129
	v_cndmask_b32_e64 v0, 0, v0, s[90:91]
	v_ldexp_f32 v2, v8, v2
	v_mul_f32_e32 v8, 0x3fb8aa3b, v4
	v_fma_f32 v9, v4, s97, -v8
	v_fmac_f32_e32 v9, 0x32a5705f, v4
	v_rndne_f32_e32 v4, v8
	v_sub_f32_e32 v8, v8, v4
	v_add_f32_e32 v8, v8, v9
	v_exp_f32_e32 v8, v8
	v_cvt_i32_f32_e32 v4, v4
	v_cndmask_b32_e64 v2, 0, v2, s[86:87]
	v_cndmask_b32_e64 v0, v181, v0, s[92:93]
	v_cndmask_b32_e64 v2, v181, v2, s[88:89]
	v_ldexp_f32 v4, v8, v4
	v_mul_f32_e32 v8, 0x3fb8aa3b, v6
	v_fma_f32 v9, v6, s97, -v8
	v_fmac_f32_e32 v9, 0x32a5705f, v6
	v_rndne_f32_e32 v6, v8
	v_sub_f32_e32 v8, v8, v6
	v_add_f32_e32 v8, v8, v9
	v_exp_f32_e32 v8, v8
	v_cvt_i32_f32_e32 v6, v6
	v_cndmask_b32_e64 v4, 0, v4, s[82:83]
	v_cndmask_b32_e64 v4, v181, v4, s[84:85]
	v_mov_b32_e32 v97, v129
	v_ldexp_f32 v6, v8, v6
	v_mul_f32_e32 v8, 0x3fb8aa3b, v1
	v_fma_f32 v9, v1, s97, -v8
	v_fmac_f32_e32 v9, 0x32a5705f, v1
	v_rndne_f32_e32 v1, v8
	v_sub_f32_e32 v8, v8, v1
	v_add_f32_e32 v8, v8, v9
	v_exp_f32_e32 v8, v8
	v_cvt_i32_f32_e32 v1, v1
	v_cndmask_b32_e64 v6, 0, v6, s[78:79]
	v_cndmask_b32_e64 v6, v181, v6, s[80:81]
	v_mov_b32_e32 v99, v129
	v_ldexp_f32 v1, v8, v1
	v_mul_f32_e32 v8, 0x3fb8aa3b, v3
	v_fma_f32 v9, v3, s97, -v8
	v_fmac_f32_e32 v9, 0x32a5705f, v3
	v_rndne_f32_e32 v3, v8
	v_sub_f32_e32 v8, v8, v3
	v_add_f32_e32 v8, v8, v9
	v_exp_f32_e32 v8, v8
	v_cvt_i32_f32_e32 v3, v3
	v_cndmask_b32_e64 v1, 0, v1, s[74:75]
	v_cndmask_b32_e64 v1, v181, v1, s[76:77]
	v_ldexp_f32 v3, v8, v3
	v_mul_f32_e32 v8, 0x3fb8aa3b, v5
	v_fma_f32 v9, v5, s97, -v8
	v_fmac_f32_e32 v9, 0x32a5705f, v5
	v_rndne_f32_e32 v5, v8
	v_sub_f32_e32 v8, v8, v5
	v_add_f32_e32 v8, v8, v9
	v_exp_f32_e32 v8, v8
	v_cvt_i32_f32_e32 v5, v5
	v_cndmask_b32_e64 v3, 0, v3, s[70:71]
	s_ashr_i32 s70, s7, 6
	s_cmp_eq_u32 s28, 0
	v_ldexp_f32 v5, v8, v5
	v_mul_f32_e32 v8, 0x3fb8aa3b, v7
	v_fma_f32 v9, v7, s97, -v8
	v_fmac_f32_e32 v9, 0x32a5705f, v7
	v_rndne_f32_e32 v7, v8
	v_sub_f32_e32 v8, v8, v7
	v_add_f32_e32 v8, v8, v9
	v_exp_f32_e32 v8, v8
	v_cvt_i32_f32_e32 v7, v7
	v_cndmask_b32_e64 v5, 0, v5, s[66:67]
	v_cndmask_b32_e64 v5, v181, v5, s[68:69]
	v_cndmask_b32_e64 v3, v181, v3, s[72:73]
	v_ldexp_f32 v7, v8, v7
	v_cndmask_b32_e32 v7, 0, v7, vcc
	v_cndmask_b32_e64 v7, v181, v7, s[64:65]
	s_cselect_b64 s[64:65], -1, 0
	s_cmp_lg_u32 s28, 0
	s_cselect_b64 s[66:67], -1, 0
	s_and_b64 s[22:23], s[64:65], exec
	s_cselect_b32 s22, s95, s13
	s_cselect_b32 s23, s94, s12
	s_ashr_i32 s71, s70, 31
	s_lshl_b64 s[24:25], s[70:71], 26
	s_add_u32 s24, s30, s24
	v_cndmask_b32_e64 v10, v119, v108, s[64:65]
	s_addc_u32 s25, s31, s25
	s_lshl_b32 s9, s9, 1
	s_add_u32 s68, s24, s9
	v_ashrrev_i32_e32 v11, 31, v10
	s_addc_u32 s69, s25, 0
	v_lshlrev_b64 v[10:11], 14, v[10:11]
	s_lshl_b32 s24, s7, 6
	v_lshl_add_u64 v[10:11], s[68:69], 0, v[10:11]
	s_lshl_b32 s28, s8, 1
	s_and_b32 s25, s24, 64
	v_lshl_add_u64 v[14:15], v[10:11], 0, s[28:29]
	v_cndmask_b32_e64 v18, v121, v120, s[64:65]
	v_or_b32_e32 v8, s25, v93
	v_lshl_add_u64 v[14:15], v[14:15], 0, v[128:129]
	v_ashrrev_i32_e32 v19, 31, v18
	v_add_co_u32_e32 v14, vcc, s1, v14
	v_lshlrev_b32_e32 v16, 1, v8
	v_lshlrev_b64 v[18:19], 14, v[18:19]
	v_lshl_add_u64 v[12:13], v[10:11], 0, v[128:129]
	v_addc_co_u32_e32 v15, vcc, 0, v15, vcc
	v_lshl_add_u64 v[10:11], v[10:11], 0, v[16:17]
	v_lshl_add_u64 v[18:19], s[68:69], 0, v[18:19]
	v_add_co_u32_e32 v10, vcc, s2, v10
	v_lshl_add_u64 v[22:23], v[18:19], 0, s[28:29]
	v_cndmask_b32_e64 v24, v123, v122, s[64:65]
	v_addc_co_u32_e32 v11, vcc, 0, v11, vcc
	v_lshl_add_u64 v[22:23], v[22:23], 0, v[128:129]
	v_ashrrev_i32_e32 v25, 31, v24
	v_add_co_u32_e32 v22, vcc, s1, v22
	v_lshlrev_b64 v[24:25], 14, v[24:25]
	v_lshl_add_u64 v[20:21], v[18:19], 0, v[128:129]
	v_addc_co_u32_e32 v23, vcc, 0, v23, vcc
	v_lshl_add_u64 v[18:19], v[18:19], 0, v[16:17]
	v_lshl_add_u64 v[24:25], s[68:69], 0, v[24:25]
	v_add_co_u32_e32 v18, vcc, s2, v18
	v_lshl_add_u64 v[28:29], v[24:25], 0, s[28:29]
	s_nop 0
	v_addc_co_u32_e32 v19, vcc, 0, v19, vcc
	v_lshl_add_u64 v[28:29], v[28:29], 0, v[128:129]
	v_add_co_u32_e32 v28, vcc, s1, v28
	v_lshl_add_u64 v[26:27], v[24:25], 0, v[128:129]
	s_nop 0
	v_addc_co_u32_e32 v29, vcc, 0, v29, vcc
	global_load_dword v144, v[12:13], off
	global_load_dword v145, v[14:15], off
	global_load_ushort v9, v[10:11], off
	global_load_dword v146, v[20:21], off
	global_load_dword v147, v[22:23], off
	global_load_ushort v36, v[18:19], off
	global_load_dword v148, v[26:27], off
	global_load_dword v149, v[28:29], off
	v_cndmask_b32_e64 v12, v125, v124, s[64:65]
	v_ashrrev_i32_e32 v13, 31, v12
	v_lshl_add_u64 v[10:11], v[24:25], 0, v[16:17]
	v_lshlrev_b64 v[12:13], 14, v[12:13]
	v_cndmask_b32_e64 v20, v127, v126, s[64:65]
	v_add_co_u32_e32 v10, vcc, s2, v10
	v_lshl_add_u64 v[12:13], s[68:69], 0, v[12:13]
	v_ashrrev_i32_e32 v21, 31, v20
	v_addc_co_u32_e32 v11, vcc, 0, v11, vcc
	v_lshl_add_u64 v[18:19], v[12:13], 0, v[16:17]
	v_lshlrev_b64 v[20:21], 14, v[20:21]
	v_add_co_u32_e32 v18, vcc, s2, v18
	v_lshl_add_u64 v[20:21], s[68:69], 0, v[20:21]
; DI f32x16 zero16() { f32x16 z; for (int i = 0; i < 16; ++i) z[i] = 0.f; return z; }
; #define HG_PREFETCH(cn) do { \
;     _Pragma("unroll") for (int e = 0; e < 8; ++e) { const bf16_t* pr = PROJ + ROWTOK(cn, seg * 8 + e) * 8192 + h * 128; \
;       rq[e] = *(const unsigned*)(pr + 2 * kp); rf[e] = *(const unsigned*)(pr + 2048 + dir * 2048 + 2 * kp); rv[e] = pr[6144 + dh * 64 + lane]; } } while (0)
; DI void hg_scan_phase(int wvs, char* smem, const bf16_t* __restrict__ PROJ, const float* __restrict__ lbraw, bf16_t* OF, bf16_t* OB) {
;     ...
;     float lbv[2];
; #pragma unroll
;     for (int u = 0; u < 2; ++u) {
;       const int idx = dir * 2048 + h * 128 + 2 * kp + u;
;       const float l0 = lbraw[idx], l1 = lbraw[4096 + idx], l2 = lbraw[8192 + idx], l3 = lbraw[12288 + idx];
;       const float mx = fmaxf(fmaxf(l0, l1), fmaxf(l2, l3));
;       const float e0 = expf(l0 - mx), e1 = expf(l1 - mx), e2 = expf(l2 - mx), e3 = expf(l3 - mx);
;       lbv[u] = (e1 + e2) / (e0 + e1 + e2 + e3);
;     }
;     const float lb0 = lbv[0], lb1 = lbv[1];
;     bf16_t* O = dir ? OB : OF;
;     f32x16 sacc = zero16();
;     const int kb = w & 3, db = w >> 2;
;     ...
;     unsigned rq[8], rf[8]; bf16_t rv[8];
;     ...
;     __syncthreads();
;     for (int e = tid; e < 64 * SD / 2; e += NT) ((unsigned*)St)[e] = 0u;
;     HG_PREFETCH(0);
	s_nop 0
	v_addc_co_u32_e32 v19, vcc, 0, v19, vcc
	v_lshl_add_u64 v[22:23], v[20:21], 0, v[16:17]
	v_add_co_u32_e32 v22, vcc, s2, v22
	v_cndmask_b32_e64 v24, v134, v133, s[64:65]
	s_nop 0
	v_addc_co_u32_e32 v23, vcc, 0, v23, vcc
	global_load_ushort v37, v[10:11], off
	global_load_ushort v38, v[18:19], off
	global_load_ushort v39, v[22:23], off
	v_cndmask_b32_e64 v10, v132, v131, s[64:65]
	v_ashrrev_i32_e32 v11, 31, v10
	v_lshlrev_b64 v[10:11], 14, v[10:11]
	v_lshl_add_u64 v[10:11], s[68:69], 0, v[10:11]
	v_lshl_add_u64 v[18:19], v[10:11], 0, s[28:29]
	v_lshl_add_u64 v[18:19], v[18:19], 0, v[128:129]
	v_ashrrev_i32_e32 v25, 31, v24
	v_add_co_u32_e32 v18, vcc, s1, v18
	v_lshlrev_b64 v[24:25], 14, v[24:25]
	s_nop 0
	v_addc_co_u32_e32 v19, vcc, 0, v19, vcc
	v_lshl_add_u64 v[22:23], v[10:11], 0, v[16:17]
	v_lshl_add_u64 v[24:25], s[68:69], 0, v[24:25]
	v_add_co_u32_e32 v22, vcc, s2, v22
	v_lshl_add_u64 v[28:29], v[24:25], 0, s[28:29]
	v_cndmask_b32_e64 v30, v136, v135, s[64:65]
	v_addc_co_u32_e32 v23, vcc, 0, v23, vcc
	v_lshl_add_u64 v[28:29], v[28:29], 0, v[128:129]
	v_ashrrev_i32_e32 v31, 31, v30
	v_add_co_u32_e32 v28, vcc, s1, v28
	v_lshlrev_b64 v[30:31], 14, v[30:31]
	v_lshl_add_u64 v[26:27], v[24:25], 0, v[128:129]
	v_addc_co_u32_e32 v29, vcc, 0, v29, vcc
	v_lshl_add_u64 v[24:25], v[24:25], 0, v[16:17]
	v_lshl_add_u64 v[30:31], s[68:69], 0, v[30:31]
	v_add_co_u32_e32 v24, vcc, s2, v24
	v_lshl_add_u64 v[34:35], v[30:31], 0, s[28:29]
	s_nop 0
	v_addc_co_u32_e32 v25, vcc, 0, v25, vcc
	v_lshl_add_u64 v[34:35], v[34:35], 0, v[128:129]
	v_add_co_u32_e32 v34, vcc, s1, v34
	v_lshl_add_u64 v[16:17], v[30:31], 0, v[16:17]
	s_nop 0
	v_addc_co_u32_e32 v35, vcc, 0, v35, vcc
	v_lshl_add_u64 v[14:15], v[12:13], 0, v[128:129]
	v_add_co_u32_e32 v16, vcc, s2, v16
	v_lshl_add_u64 v[12:13], v[12:13], 0, s[28:29]
	s_nop 0
	v_addc_co_u32_e32 v17, vcc, 0, v17, vcc
	v_lshl_add_u64 v[12:13], v[12:13], 0, v[128:129]
	v_lshl_add_u64 v[32:33], v[30:31], 0, v[128:129]
	global_load_dword v154, v[18:19], off
	s_nop 0
	global_load_ushort v22, v[22:23], off
	s_nop 0
	global_load_dword v156, v[26:27], off
	global_load_dword v157, v[28:29], off
	global_load_ushort v23, v[24:25], off
	global_load_dword v158, v[32:33], off
	global_load_dword v159, v[34:35], off
	s_nop 0
	global_load_ushort v24, v[16:17], off
	v_add_co_u32_e32 v12, vcc, s1, v12
	v_lshl_add_u64 v[18:19], v[20:21], 0, s[28:29]
	s_nop 0
	v_addc_co_u32_e32 v13, vcc, 0, v13, vcc
	v_lshl_add_u64 v[18:19], v[18:19], 0, v[128:129]
	v_add_co_u32_e32 v18, vcc, s1, v18
	v_lshl_add_u64 v[16:17], v[20:21], 0, v[128:129]
	s_nop 0
	v_addc_co_u32_e32 v19, vcc, 0, v19, vcc
	v_lshl_add_u64 v[10:11], v[10:11], 0, v[128:129]
	global_load_dword v150, v[14:15], off
	global_load_dword v152, v[16:17], off
	global_load_dword v155, v[10:11], off
	global_load_dword v153, v[18:19], off
	global_load_dword v151, v[12:13], off
	v_pk_add_f32 v[0:1], v[0:1], v[2:3]
	v_pk_add_f32 v[10:11], v[2:3], v[4:5]
	v_pk_add_f32 v[0:1], v[4:5], v[0:1]
	s_lshl_b64 s[70:71], s[70:71], 24
	v_pk_add_f32 v[0:1], v[6:7], v[0:1]
	s_add_u32 s23, s23, s70
	v_div_scale_f32 v2, s[72:73], v1, v1, v11
	v_rcp_f32_e32 v3, v2
	s_addc_u32 s22, s22, s71
	s_add_u32 s9, s23, s9
	s_addc_u32 s23, s22, 0
	v_fma_f32 v4, -v2, v3, 1.0
	v_fmac_f32_e32 v3, v4, v3
	v_div_scale_f32 v4, vcc, v11, v1, v11
	v_mul_f32_e32 v5, v4, v3
	v_fma_f32 v6, -v2, v5, v4
	v_fmac_f32_e32 v5, v6, v3
	v_fma_f32 v2, -v2, v5, v4
	v_div_scale_f32 v4, s[72:73], v0, v0, v10
	v_rcp_f32_e32 v6, v4
	v_div_fmas_f32 v2, v2, v3, v5
	v_div_fixup_f32 v101, v2, v1, v11
	s_lshl_b32 s22, s25, 1
	v_fma_f32 v1, -v4, v6, 1.0
	v_fmac_f32_e32 v6, v1, v6
	v_div_scale_f32 v1, vcc, v10, v0, v10
	v_mul_f32_e32 v2, v1, v6
	v_fma_f32 v3, -v4, v2, v1
	v_fmac_f32_e32 v2, v3, v6
	v_fma_f32 v1, -v4, v2, v1
	s_add_u32 s22, s9, s22
	v_div_fmas_f32 v1, v1, v6, v2
	s_addc_u32 s23, s23, 0
	v_div_fixup_f32 v100, v1, v0, v10
	v_lshl_add_u64 v[0:1], s[22:23], 0, v[96:97]
	v_lshl_add_u64 v[104:105], v[0:1], 0, v[98:99]
	v_mov_b32_e32 v0, 0
	s_mov_b32 s24, 0
	v_pk_add_f32 v[102:103], v[100:101], 1.0 op_sel_hi:[1,0] neg_lo:[1,0] neg_hi:[1,0]
	s_waitcnt vmcnt(18)
	v_perm_b32 v48, v36, v9, s3
	s_waitcnt vmcnt(14)
	v_perm_b32 v49, v38, v37, s3
	s_lshl_b32 s28, s8, 1
	v_lshlrev_b32_e32 v106, 1, v8
	v_mov_b32_e32 v1, v0
	v_mov_b32_e32 v2, v0
	v_mov_b32_e32 v3, v0
	v_mov_b32_e32 v4, v0
	v_mov_b32_e32 v5, v0
	v_mov_b32_e32 v6, v0
	v_mov_b32_e32 v7, v0
	v_mov_b32_e32 v8, v0
	v_mov_b32_e32 v9, v0
	v_mov_b32_e32 v10, v0
	v_mov_b32_e32 v11, v0
	v_mov_b32_e32 v12, v0
	v_mov_b32_e32 v13, v0
	s_waitcnt vmcnt(11)
	v_perm_b32 v50, v22, v39, s3
	v_mov_b32_e32 v14, v0
	v_mov_b32_e32 v15, v0
	s_waitcnt vmcnt(5)
	v_perm_b32 v51, v24, v23, s3
	v_add_u32_e32 v240, 64, v108
	v_sub_u32_e32 v241, 0xfff, v240
	v_cndmask_b32_e64 v240, v241, v240, s[64:65]
	v_ashrrev_i32_e32 v241, 31, v240
	v_lshlrev_b64 v[240:241], 14, v[240:241]
	v_lshl_add_u64 v[240:241], s[68:69], 0, v[240:241]
	v_lshl_add_u64 v[230:231], v[240:241], 0, v[128:129]
	v_mov_b32_e32 v232, 0xffffc000
	v_mov_b32_e32 v233, -1
	v_mov_b32_e32 v240, 0x4000
	v_cndmask_b32_e64 v232, v232, v240, s[64:65]
	v_cndmask_b32_e64 v233, v233, 0, s[64:65]
	v_mov_b32_e32 v234, 0xfff1c000
	v_mov_b32_e32 v240, 0xe4000
	v_cndmask_b32_e64 v234, v234, v240, s[64:65]
	v_mov_b32_e32 v235, v233
	v_mov_b32_e32 v236, s28
	v_mov_b32_e32 v237, s29
	v_add_co_u32_e32 v236, vcc, s1, v236
	s_nop 1
	v_addc_co_u32_e32 v237, vcc, 0, v237, vcc
	v_sub_co_u32_e32 v238, vcc, v106, v128
	s_nop 1
	v_subb_co_u32_e32 v239, vcc, 0, v129, vcc
	v_add_co_u32_e32 v238, vcc, s2, v238
	s_nop 1
	v_addc_co_u32_e32 v239, vcc, 0, v239, vcc
	s_waitcnt vmcnt(0)
	s_branch .LBB0_378

; #define HG_PREFETCH(cn) do { \
;     _Pragma("unroll") for (int e = 0; e < 8; ++e) { const bf16_t* pr = PROJ + ROWTOK(cn, seg * 8 + e) * 8192 + h * 128; \
;       rq[e] = *(const unsigned*)(pr + 2 * kp); rf[e] = *(const unsigned*)(pr + 2048 + dir * 2048 + 2 * kp); rv[e] = pr[6144 + dh * 64 + lane]; } } while (0)
; DI void hg_scan_phase(int wvs, char* smem, const bf16_t* __restrict__ PROJ, const float* __restrict__ lbraw, bf16_t* OF, bf16_t* OB) {
;     ...
;     __syncthreads();
;     for (int e = tid; e < 64 * SD / 2; e += NT) ((unsigned*)St)[e] = 0u;
;     HG_PREFETCH(0);
;     ...
;       if (ci + 1 < 64) HG_PREFETCH(ci + 1);
.LBB0_378:
	s_cmp_eq_u32 s24, 63
	s_cbranch_scc1 .Lhg_nopf
	s_add_i32 s25, s24, 1
	global_load_dword v200, v[230:231], off
	v_lshl_add_u64 v[240:241], v[230:231], 0, v[236:237]
	v_lshl_add_u64 v[242:243], v[230:231], 0, v[238:239]
	global_load_dword v201, v[240:241], off
	global_load_ushort v221, v[242:243], off
	v_lshl_add_u64 v[230:231], v[230:231], 0, v[232:233]
	global_load_dword v202, v[230:231], off
	v_lshl_add_u64 v[240:241], v[230:231], 0, v[236:237]
	v_lshl_add_u64 v[242:243], v[230:231], 0, v[238:239]
	global_load_dword v203, v[240:241], off
	global_load_ushort v222, v[242:243], off
	v_lshl_add_u64 v[230:231], v[230:231], 0, v[232:233]
	global_load_dword v204, v[230:231], off
	v_lshl_add_u64 v[240:241], v[230:231], 0, v[236:237]
	v_lshl_add_u64 v[242:243], v[230:231], 0, v[238:239]
	global_load_dword v205, v[240:241], off
	global_load_ushort v223, v[242:243], off
	v_lshl_add_u64 v[230:231], v[230:231], 0, v[232:233]
	global_load_dword v206, v[230:231], off
	v_lshl_add_u64 v[240:241], v[230:231], 0, v[236:237]
	v_lshl_add_u64 v[242:243], v[230:231], 0, v[238:239]
	global_load_dword v207, v[240:241], off
	global_load_ushort v224, v[242:243], off
	v_lshl_add_u64 v[230:231], v[230:231], 0, v[232:233]
	global_load_dword v208, v[230:231], off
	v_lshl_add_u64 v[240:241], v[230:231], 0, v[236:237]
	v_lshl_add_u64 v[242:243], v[230:231], 0, v[238:239]
	global_load_dword v209, v[240:241], off
	global_load_ushort v225, v[242:243], off
	v_lshl_add_u64 v[230:231], v[230:231], 0, v[232:233]
	global_load_dword v216, v[230:231], off
	v_lshl_add_u64 v[240:241], v[230:231], 0, v[236:237]
	v_lshl_add_u64 v[242:243], v[230:231], 0, v[238:239]
	global_load_dword v215, v[240:241], off
	global_load_ushort v226, v[242:243], off
	v_lshl_add_u64 v[230:231], v[230:231], 0, v[232:233]
	global_load_dword v217, v[230:231], off
	v_lshl_add_u64 v[240:241], v[230:231], 0, v[236:237]
	v_lshl_add_u64 v[242:243], v[230:231], 0, v[238:239]
	global_load_dword v218, v[240:241], off
	global_load_ushort v227, v[242:243], off
	v_lshl_add_u64 v[230:231], v[230:231], 0, v[232:233]
	global_load_dword v219, v[230:231], off
	v_lshl_add_u64 v[240:241], v[230:231], 0, v[236:237]
	v_lshl_add_u64 v[242:243], v[230:231], 0, v[238:239]
	global_load_dword v220, v[240:241], off
	global_load_ushort v228, v[242:243], off
	v_lshl_add_u64 v[230:231], v[230:231], 0, v[234:235]
